# E35: E33 + s_setprio toggling also removed from the prompt-attention tiles
# speedup vs baseline: 1.0060x; 1.0005x over previous
.LBB0_4411:
	s_lshl_b32 s1, 1, s0
	s_and_b32 s2, s96, s1
	s_cmp_eq_u32 s2, 0
	s_cbranch_scc1 .LBB0_4427
	s_and_b32 s1, s1, s84
	s_cmp_lg_u32 s1, 0
	s_cselect_b64 s[90:91], -1, 0
	s_mul_i32 s72, s75, 0x1200
	v_lshl_add_u32 v3, s72, 1, v99
	ds_read_b128 v[62:65], v3 offset:35904
	ds_read_b128 v[66:69], v3 offset:35968
	ds_read_b128 v[78:81], v3 offset:40512
	ds_read_b128 v[196:199], v3 offset:42816
	s_waitcnt lgkmcnt(3)
	v_mfma_f32_16x16x32_bf16 v[70:73], v[62:65], v[6:9], 0
	v_mfma_f32_16x16x32_bf16 v[62:65], v[62:65], v[14:17], 0
	s_waitcnt lgkmcnt(2)
	v_mfma_f32_16x16x32_bf16 v[90:93], v[66:69], v[10:13], v[70:73]
	s_nop 4
	ds_read_b128 v[70:73], v3 offset:38208
	v_mfma_f32_16x16x32_bf16 v[74:77], v[66:69], v[18:21], v[62:65]
	s_nop 2
	ds_read_b128 v[62:65], v3 offset:38272
	s_waitcnt lgkmcnt(1)
	v_mfma_f32_16x16x32_bf16 v[66:69], v[70:73], v[6:9], 0
	s_waitcnt lgkmcnt(0)
	v_mfma_f32_16x16x32_bf16 v[86:89], v[62:65], v[10:13], v[66:69]
	v_mfma_f32_16x16x32_bf16 v[66:69], v[70:73], v[14:17], 0
	v_mfma_f32_16x16x32_bf16 v[70:73], v[62:65], v[18:21], v[66:69]
	ds_read_b128 v[62:65], v3 offset:40576
	v_mfma_f32_16x16x32_bf16 v[66:69], v[78:81], v[6:9], 0
	s_waitcnt lgkmcnt(0)
	v_mfma_f32_16x16x32_bf16 v[82:85], v[62:65], v[10:13], v[66:69]
	v_mfma_f32_16x16x32_bf16 v[66:69], v[78:81], v[14:17], 0
	v_mfma_f32_16x16x32_bf16 v[66:69], v[62:65], v[18:21], v[66:69]
	ds_read_b128 v[62:65], v3 offset:42880
	v_mfma_f32_16x16x32_bf16 v[78:81], v[196:199], v[6:9], 0
	v_mfma_f32_16x16x32_bf16 v[196:199], v[196:199], v[14:17], 0
	s_waitcnt lgkmcnt(0)
	v_mfma_f32_16x16x32_bf16 v[78:81], v[62:65], v[10:13], v[78:81]
	v_mfma_f32_16x16x32_bf16 v[62:65], v[62:65], v[18:21], v[196:199]
	v_lshl_add_u32 v3, s0, 6, v219
	v_sub_u32_e32 v238, v104, v3
	v_cvt_f32_i32_e32 v239, v238
	s_and_b64 vcc, exec, s[90:91]
	v_mul_f32_e64 v212, -v123, v239
	s_cbranch_vccz .LBB0_4414
	v_pk_add_f32 v[196:197], v[212:213], v[90:91] op_sel_hi:[0,1]
	v_pk_add_f32 v[196:197], v[122:123], v[196:197]
	v_pk_add_f32 v[198:199], v[212:213], v[92:93] op_sel_hi:[0,1]
	v_max3_f32 v3, v196, s93, v197
	v_pk_add_f32 v[198:199], v[124:125], v[198:199]
	v_pk_add_f32 v[200:201], v[212:213], v[86:87] op_sel_hi:[0,1]
	v_max3_f32 v3, v3, v198, v199
	v_pk_add_f32 v[200:201], v[126:127], v[200:201]
	v_pk_add_f32 v[202:203], v[212:213], v[88:89] op_sel_hi:[0,1]
	v_max3_f32 v3, v3, v200, v201
	v_pk_add_f32 v[202:203], v[128:129], v[202:203]
	v_pk_add_f32 v[204:205], v[212:213], v[82:83] op_sel_hi:[0,1]
	v_max3_f32 v3, v3, v202, v203
	v_pk_add_f32 v[204:205], v[130:131], v[204:205]
	v_pk_add_f32 v[206:207], v[212:213], v[84:85] op_sel_hi:[0,1]
	v_max3_f32 v3, v3, v204, v205
	v_pk_add_f32 v[206:207], v[132:133], v[206:207]
	v_pk_add_f32 v[208:209], v[212:213], v[78:79] op_sel_hi:[0,1]
	v_max3_f32 v3, v3, v206, v207
	v_pk_add_f32 v[208:209], v[134:135], v[208:209]
	v_pk_add_f32 v[210:211], v[212:213], v[80:81] op_sel_hi:[0,1]
	v_max3_f32 v3, v3, v208, v209
	v_pk_add_f32 v[210:211], v[136:137], v[210:211]
	s_mov_b64 s[0:1], 0
	v_max3_f32 v3, v3, v210, v211
	s_branch .LBB0_4417

.LBB0_4426:
	v_sub_f32_e32 v4, v4, v78
	v_exp_f32_e32 v4, v4
	s_nop 0
	v_pk_mul_f32 v[52:53], v[52:53], v[4:5] op_sel_hi:[1,0]
	v_pk_mul_f32 v[50:51], v[50:51], v[4:5] op_sel_hi:[1,0]
	v_pk_mul_f32 v[48:49], v[48:49], v[4:5] op_sel_hi:[1,0]
	v_pk_mul_f32 v[46:47], v[46:47], v[4:5] op_sel_hi:[1,0]
	v_pk_mul_f32 v[44:45], v[44:45], v[4:5] op_sel_hi:[1,0]
	v_sub_f32_e32 v5, v5, v79
	v_exp_f32_e32 v82, v5
	v_pk_mul_f32 v[42:43], v[42:43], v[4:5] op_sel_hi:[1,0]
	v_pk_mul_f32 v[40:41], v[40:41], v[4:5] op_sel_hi:[1,0]
	v_pk_mul_f32 v[38:39], v[38:39], v[4:5] op_sel_hi:[1,0]
	v_pk_mul_f32 v[36:37], v[36:37], v[82:83] op_sel_hi:[1,0]
	v_pk_mul_f32 v[34:35], v[34:35], v[82:83] op_sel_hi:[1,0]
	v_pk_mul_f32 v[32:33], v[32:33], v[82:83] op_sel_hi:[1,0]
	v_pk_mul_f32 v[30:31], v[30:31], v[82:83] op_sel_hi:[1,0]
	v_pk_mul_f32 v[28:29], v[28:29], v[82:83] op_sel_hi:[1,0]
	v_pk_mul_f32 v[26:27], v[26:27], v[82:83] op_sel_hi:[1,0]
	v_pk_mul_f32 v[24:25], v[24:25], v[82:83] op_sel_hi:[1,0]
	v_pk_mul_f32 v[22:23], v[22:23], v[82:83] op_sel_hi:[1,0]
	v_fmac_f32_e32 v80, v194, v4
	v_fmac_f32_e32 v81, v195, v82
	v_lshl_add_u32 v4, s72, 1, v101
	v_add_u32_e32 v5, 0xd000, v4
	v_cvt_pk_bf16_f32 v70, v70, v71
	v_cvt_pk_bf16_f32 v71, v72, v74
	v_cvt_pk_bf16_f32 v72, v73, v75
	v_cvt_pk_bf16_f32 v73, v76, v77
	ds_read2_b64 v[74:77], v5 offset0:136 offset1:140
	v_add_u32_e32 v86, 0xd800, v4
	v_cvt_pk_bf16_f32 v82, v230, v231
	v_cvt_pk_bf16_f32 v83, v232, v234
	v_cvt_pk_bf16_f32 v84, v233, v235
	v_cvt_pk_bf16_f32 v85, v236, v237
	s_waitcnt lgkmcnt(0)
	v_mfma_f32_16x16x32_bf16 v[34:37], v[74:77], v[70:73], v[34:37]
	v_add_u32_e32 v87, 0xe000, v4
	v_add_u32_e32 v4, 0xe800, v4
	v_cvt_pk_bf16_f32 v62, v62, v63
	v_mfma_f32_16x16x32_bf16 v[50:53], v[74:77], v[82:85], v[50:53]
	ds_read2_b64 v[74:77], v86 offset0:168 offset1:172
	v_cvt_pk_bf16_f32 v63, v64, v66
	v_cvt_pk_bf16_f32 v64, v65, v67
	s_waitcnt lgkmcnt(0)
	v_mfma_f32_16x16x32_bf16 v[46:49], v[74:77], v[82:85], v[46:49]
	v_cvt_pk_bf16_f32 v65, v68, v69
	ds_read2_b64 v[66:69], v5 offset0:144 offset1:148
	v_mfma_f32_16x16x32_bf16 v[30:33], v[74:77], v[70:73], v[30:33]
	ds_read2_b64 v[74:77], v87 offset0:200 offset1:204
	s_waitcnt lgkmcnt(0)
	v_mfma_f32_16x16x32_bf16 v[42:45], v[74:77], v[82:85], v[42:45]
	v_mfma_f32_16x16x32_bf16 v[26:29], v[74:77], v[70:73], v[26:29]
	ds_read2_b64 v[74:77], v4 offset0:232 offset1:236
	s_waitcnt lgkmcnt(0)
	v_mfma_f32_16x16x32_bf16 v[22:25], v[74:77], v[70:73], v[22:25]
	v_cvt_pk_bf16_f32 v70, v3, v103
	v_cvt_pk_bf16_f32 v71, v212, v224
	v_cvt_pk_bf16_f32 v72, v223, v225
	v_cvt_pk_bf16_f32 v73, v228, v229
	v_mfma_f32_16x16x32_bf16 v[34:37], v[66:69], v[62:65], v[34:37]
	v_mfma_f32_16x16x32_bf16 v[50:53], v[66:69], v[70:73], v[50:53]
	ds_read2_b64 v[66:69], v86 offset0:176 offset1:180
	s_waitcnt lgkmcnt(0)
	v_mfma_f32_16x16x32_bf16 v[46:49], v[66:69], v[70:73], v[46:49]
	v_mfma_f32_16x16x32_bf16 v[30:33], v[66:69], v[62:65], v[30:33]
	ds_read2_b64 v[66:69], v87 offset0:208 offset1:212
	s_waitcnt lgkmcnt(0)
	v_mfma_f32_16x16x32_bf16 v[42:45], v[66:69], v[70:73], v[42:45]
	v_mfma_f32_16x16x32_bf16 v[26:29], v[66:69], v[62:65], v[26:29]
	ds_read2_b64 v[66:69], v4 offset0:240 offset1:244
	v_mfma_f32_16x16x32_bf16 v[38:41], v[74:77], v[82:85], v[38:41]
	s_waitcnt lgkmcnt(0)
	v_mfma_f32_16x16x32_bf16 v[38:41], v[66:69], v[70:73], v[38:41]
	v_mfma_f32_16x16x32_bf16 v[22:25], v[66:69], v[62:65], v[22:25]
	v_mov_b64_e32 v[194:195], v[80:81]
	v_mov_b64_e32 v[4:5], v[78:79]

.LBB0_4441:
	s_lshl_b32 s1, 1, s0
	s_and_b32 s2, s1, s95
	s_cmp_eq_u32 s2, 0
	s_cbranch_scc1 .LBB0_4457
	s_and_b32 s2, s92, s1
	s_cmp_lg_u32 s2, 0
	s_cselect_b64 s[38:39], -1, 0
	s_mul_i32 s43, s40, 0x1200
	v_and_b32_e32 v3, s1, v1
	v_lshl_add_u32 v103, s43, 1, v99
	ds_read_b128 v[62:65], v103 offset:35904
	ds_read_b128 v[66:69], v103 offset:35968
	ds_read_b128 v[78:81], v103 offset:40512
	ds_read_b128 v[196:199], v103 offset:42816
	v_cmp_eq_u32_e64 s[4:5], 0, v3
	s_waitcnt lgkmcnt(3)
	v_mfma_f32_16x16x32_bf16 v[70:73], v[62:65], v[6:9], 0
	v_mfma_f32_16x16x32_bf16 v[62:65], v[62:65], v[14:17], 0
	s_waitcnt lgkmcnt(2)
	v_mfma_f32_16x16x32_bf16 v[90:93], v[66:69], v[10:13], v[70:73]
	s_nop 4
	ds_read_b128 v[70:73], v103 offset:38208
	v_mfma_f32_16x16x32_bf16 v[74:77], v[66:69], v[18:21], v[62:65]
	s_nop 2
	ds_read_b128 v[62:65], v103 offset:38272
	s_waitcnt lgkmcnt(1)
	v_mfma_f32_16x16x32_bf16 v[66:69], v[70:73], v[6:9], 0
	s_waitcnt lgkmcnt(0)
	v_mfma_f32_16x16x32_bf16 v[86:89], v[62:65], v[10:13], v[66:69]
	v_mfma_f32_16x16x32_bf16 v[66:69], v[70:73], v[14:17], 0
	v_mfma_f32_16x16x32_bf16 v[70:73], v[62:65], v[18:21], v[66:69]
	ds_read_b128 v[62:65], v103 offset:40576
	v_mfma_f32_16x16x32_bf16 v[66:69], v[78:81], v[6:9], 0
	s_waitcnt lgkmcnt(0)
	v_mfma_f32_16x16x32_bf16 v[82:85], v[62:65], v[10:13], v[66:69]
	v_mfma_f32_16x16x32_bf16 v[66:69], v[78:81], v[14:17], 0
	v_mfma_f32_16x16x32_bf16 v[66:69], v[62:65], v[18:21], v[66:69]
	ds_read_b128 v[62:65], v103 offset:42880
	v_mfma_f32_16x16x32_bf16 v[78:81], v[196:199], v[6:9], 0
	v_mfma_f32_16x16x32_bf16 v[196:199], v[196:199], v[14:17], 0
	s_waitcnt lgkmcnt(0)
	v_mfma_f32_16x16x32_bf16 v[78:81], v[62:65], v[10:13], v[78:81]
	v_mfma_f32_16x16x32_bf16 v[62:65], v[62:65], v[18:21], v[196:199]
	v_lshl_add_u32 v3, s0, 6, v219
	v_sub_u32_e32 v236, v104, v3
	v_cvt_f32_i32_e32 v237, v236
	s_and_b64 vcc, exec, s[38:39]
	v_mul_f32_e64 v210, -v123, v237
	v_fma_f32 v3, -v123, v237, v90
	v_add_f32_e32 v90, v122, v3
	v_add_f32_e32 v3, v210, v93
	s_cbranch_vccz .LBB0_4444
	v_mov_b32_e32 v196, v91
	v_mov_b32_e32 v197, v92
	v_pk_add_f32 v[196:197], v[210:211], v[196:197] op_sel_hi:[0,1]
	v_pk_add_f32 v[196:197], v[192:193], v[196:197]
	v_add_f32_e32 v93, v125, v3
	v_max3_f32 v103, v90, s93, v196
	v_pk_add_f32 v[198:199], v[210:211], v[86:87] op_sel_hi:[0,1]
	v_max3_f32 v103, v103, v197, v93
	v_pk_add_f32 v[198:199], v[126:127], v[198:199]
	v_pk_add_f32 v[200:201], v[210:211], v[88:89] op_sel_hi:[0,1]
	v_max3_f32 v103, v103, v198, v199
	v_pk_add_f32 v[200:201], v[128:129], v[200:201]
	v_pk_add_f32 v[202:203], v[210:211], v[82:83] op_sel_hi:[0,1]
	v_max3_f32 v103, v103, v200, v201
	v_pk_add_f32 v[202:203], v[130:131], v[202:203]
	v_pk_add_f32 v[204:205], v[210:211], v[84:85] op_sel_hi:[0,1]
	v_max3_f32 v103, v103, v202, v203
	v_pk_add_f32 v[204:205], v[132:133], v[204:205]
	v_pk_add_f32 v[206:207], v[210:211], v[78:79] op_sel_hi:[0,1]
	v_max3_f32 v103, v103, v204, v205
	v_pk_add_f32 v[206:207], v[134:135], v[206:207]
	v_pk_add_f32 v[208:209], v[210:211], v[80:81] op_sel_hi:[0,1]
	v_max3_f32 v103, v103, v206, v207
	v_pk_add_f32 v[208:209], v[136:137], v[208:209]
	s_mov_b64 s[0:1], 0
	v_max3_f32 v103, v103, v208, v209
	s_branch .LBB0_4447

.LBB0_4456:
	v_sub_f32_e32 v4, v4, v78
	v_exp_f32_e32 v4, v4
	s_nop 0
	v_pk_mul_f32 v[52:53], v[52:53], v[4:5] op_sel_hi:[1,0]
	v_pk_mul_f32 v[50:51], v[50:51], v[4:5] op_sel_hi:[1,0]
	v_pk_mul_f32 v[48:49], v[48:49], v[4:5] op_sel_hi:[1,0]
	v_pk_mul_f32 v[46:47], v[46:47], v[4:5] op_sel_hi:[1,0]
	v_pk_mul_f32 v[44:45], v[44:45], v[4:5] op_sel_hi:[1,0]
	v_sub_f32_e32 v5, v5, v79
	v_exp_f32_e32 v74, v5
	v_pk_mul_f32 v[42:43], v[42:43], v[4:5] op_sel_hi:[1,0]
	v_pk_mul_f32 v[40:41], v[40:41], v[4:5] op_sel_hi:[1,0]
	v_pk_mul_f32 v[38:39], v[38:39], v[4:5] op_sel_hi:[1,0]
	v_pk_mul_f32 v[36:37], v[36:37], v[74:75] op_sel_hi:[1,0]
	v_pk_mul_f32 v[34:35], v[34:35], v[74:75] op_sel_hi:[1,0]
	v_pk_mul_f32 v[32:33], v[32:33], v[74:75] op_sel_hi:[1,0]
	v_pk_mul_f32 v[30:31], v[30:31], v[74:75] op_sel_hi:[1,0]
	v_pk_mul_f32 v[28:29], v[28:29], v[74:75] op_sel_hi:[1,0]
	v_pk_mul_f32 v[26:27], v[26:27], v[74:75] op_sel_hi:[1,0]
	v_pk_mul_f32 v[24:25], v[24:25], v[74:75] op_sel_hi:[1,0]
	v_pk_mul_f32 v[22:23], v[22:23], v[74:75] op_sel_hi:[1,0]
	v_fmac_f32_e32 v80, v194, v4
	v_fmac_f32_e32 v81, v195, v74
	v_lshl_add_u32 v4, s43, 1, v101
	v_add_u32_e32 v5, 0xd000, v4
	v_cvt_pk_bf16_f32 v70, v70, v71
	v_cvt_pk_bf16_f32 v71, v72, v75
	v_cvt_pk_bf16_f32 v72, v73, v76
	ds_read2_b64 v[74:77], v5 offset0:136 offset1:140
	v_add_u32_e32 v86, 0xd800, v4
	v_cvt_pk_bf16_f32 v82, v228, v229
	v_cvt_pk_bf16_f32 v83, v230, v232
	v_cvt_pk_bf16_f32 v84, v231, v233
	v_cvt_pk_bf16_f32 v85, v234, v235
	v_cvt_pk_bf16_f32 v73, v198, v199
	v_add_u32_e32 v87, 0xe000, v4
	s_waitcnt lgkmcnt(0)
	v_mfma_f32_16x16x32_bf16 v[50:53], v[74:77], v[82:85], v[50:53]
	v_add_u32_e32 v4, 0xe800, v4
	v_cvt_pk_bf16_f32 v62, v62, v63
	v_cvt_pk_bf16_f32 v63, v64, v66
	v_mfma_f32_16x16x32_bf16 v[34:37], v[74:77], v[70:73], v[34:37]
	ds_read2_b64 v[74:77], v86 offset0:168 offset1:172
	v_cvt_pk_bf16_f32 v64, v65, v67
	v_cvt_pk_bf16_f32 v65, v68, v69
	s_waitcnt lgkmcnt(0)
	v_mfma_f32_16x16x32_bf16 v[46:49], v[74:77], v[82:85], v[46:49]
	ds_read2_b64 v[66:69], v5 offset0:144 offset1:148
	v_mfma_f32_16x16x32_bf16 v[30:33], v[74:77], v[70:73], v[30:33]
	ds_read2_b64 v[74:77], v87 offset0:200 offset1:204
	s_waitcnt lgkmcnt(0)
	v_mfma_f32_16x16x32_bf16 v[42:45], v[74:77], v[82:85], v[42:45]
	v_mfma_f32_16x16x32_bf16 v[26:29], v[74:77], v[70:73], v[26:29]
	ds_read2_b64 v[74:77], v4 offset0:232 offset1:236
	s_waitcnt lgkmcnt(0)
	v_mfma_f32_16x16x32_bf16 v[22:25], v[74:77], v[70:73], v[22:25]
	v_cvt_pk_bf16_f32 v70, v3, v103
	v_cvt_pk_bf16_f32 v71, v210, v212
	v_cvt_pk_bf16_f32 v72, v211, v223
	v_cvt_pk_bf16_f32 v73, v224, v225
	v_mfma_f32_16x16x32_bf16 v[34:37], v[66:69], v[62:65], v[34:37]
	v_mfma_f32_16x16x32_bf16 v[50:53], v[66:69], v[70:73], v[50:53]
	ds_read2_b64 v[66:69], v86 offset0:176 offset1:180
	s_waitcnt lgkmcnt(0)
	v_mfma_f32_16x16x32_bf16 v[46:49], v[66:69], v[70:73], v[46:49]
	v_mfma_f32_16x16x32_bf16 v[30:33], v[66:69], v[62:65], v[30:33]
	ds_read2_b64 v[66:69], v87 offset0:208 offset1:212
	s_waitcnt lgkmcnt(0)
	v_mfma_f32_16x16x32_bf16 v[42:45], v[66:69], v[70:73], v[42:45]
	v_mfma_f32_16x16x32_bf16 v[26:29], v[66:69], v[62:65], v[26:29]
	ds_read2_b64 v[66:69], v4 offset0:240 offset1:244
	v_mfma_f32_16x16x32_bf16 v[38:41], v[74:77], v[82:85], v[38:41]
	s_waitcnt lgkmcnt(0)
	v_mfma_f32_16x16x32_bf16 v[38:41], v[66:69], v[70:73], v[38:41]
	v_mfma_f32_16x16x32_bf16 v[22:25], v[66:69], v[62:65], v[22:25]
	v_mov_b64_e32 v[194:195], v[80:81]
	v_mov_b64_e32 v[4:5], v[78:79]
